# grid barrier spin loops poll every ~256 cycles instead of ~64 (less polling traffic while the last workgroups of a phase finish)
# baseline (speedup 1.0000x reference)
; DI unsigned char* WSP(const Params& P) { size_t z = 0; asm volatile("" : "+s"(z)); return P.ws + z; }
; __global__ void __launch_bounds__(256, LB2) fwd_megakernel(Params P) {
;     ...
;   unsigned* cnt = (unsigned*)(WSP(P) + WS_CNT);
;   const int xcd = (int)(__builtin_amdgcn_s_getreg((3 << 11) | 20) & 0xF) & 7;
;   __shared__ int s_rank;
;   if (threadIdx.x == 0) s_rank = (int)atomicAdd(cnt + 900 + xcd, 1u);
;   __syncthreads();
;   const int xrank = s_rank;
;     ...
;     if (rep + 1 < nrep) grid.sync();
;     }
;     if (ph + 1 < P.ph_hi) grid.sync();
.Lgb_census:
	global_load_dword v251, v252, s[2:3] offset:3600 sc1
	s_mov_b32 s4, 0
	s_mov_b32 s5, 0
	s_waitcnt vmcnt(0)
	v_readlane_b32 s99, v251, 0
	s_add_u32 s4, s4, s99
	s_cmp_lg_u32 s99, 0
	s_addc_u32 s5, s5, 0
	v_readlane_b32 s99, v251, 1
	s_add_u32 s4, s4, s99
	s_cmp_lg_u32 s99, 0
	s_addc_u32 s5, s5, 0
	v_readlane_b32 s99, v251, 2
	s_add_u32 s4, s4, s99
	s_cmp_lg_u32 s99, 0
	s_addc_u32 s5, s5, 0
	v_readlane_b32 s99, v251, 3
	s_add_u32 s4, s4, s99
	s_cmp_lg_u32 s99, 0
	s_addc_u32 s5, s5, 0
	v_readlane_b32 s99, v251, 4
	s_add_u32 s4, s4, s99
	s_cmp_lg_u32 s99, 0
	s_addc_u32 s5, s5, 0
	v_readlane_b32 s99, v251, 5
	s_add_u32 s4, s4, s99
	s_cmp_lg_u32 s99, 0
	s_addc_u32 s5, s5, 0
	v_readlane_b32 s99, v251, 6
	s_add_u32 s4, s4, s99
	s_cmp_lg_u32 s99, 0
	s_addc_u32 s5, s5, 0
	v_readlane_b32 s99, v251, 7
	s_add_u32 s4, s4, s99
	s_cmp_lg_u32 s99, 0
	s_addc_u32 s5, s5, 0
	s_cmp_eq_u32 s4, s9
	s_cbranch_scc1 .Lgb_census_done
	s_sleep 4
	s_add_u32 s98, s98, 1
	s_cmp_lt_u32 s98, 0x40000
	s_cbranch_scc1 .Lgb_census

; __global__ void __launch_bounds__(256, LB2) fwd_megakernel(Params P) {
;     ...
;     if (ph + 1 < P.ph_hi) grid.sync();
.Lgb_wait_local:
	s_sleep 4
	global_load_dword v251, v249, s[2:3] offset:1792 sc1
	s_waitcnt vmcnt(0)
	v_readfirstlane_b32 s8, v251
	s_cmp_ge_u32 s8, s7
	s_cbranch_scc1 .Lgb_done
	s_add_u32 s98, s98, 1
	s_cmp_lt_u32 s98, 0x40000
	s_cbranch_scc1 .Lgb_wait_local
	s_branch .Lgb_done

; __global__ void __launch_bounds__(256, LB2) fwd_megakernel(Params P) {
;     ...
;     if (ph + 1 < P.ph_hi) grid.sync();
.Lgb_wait_top:
	s_sleep 4
	global_load_dword v251, v163, s[2:3] offset:2944 sc1
	s_waitcnt vmcnt(0)
	v_readfirstlane_b32 s8, v251
	s_cmp_ge_u32 s8, s7
	s_cbranch_scc1 .Lgb_release
	s_add_u32 s98, s98, 1
	s_cmp_lt_u32 s98, 0x40000
	s_cbranch_scc1 .Lgb_wait_top
	s_branch .Lgb_release
